# per-CU invalidate barrier (guarded) with an 8-byte placement pad before the phase loop
# speedup vs baseline: 1.0071x; 1.0071x over previous
; #define LAS __attribute__((address_space(3)))
; __device__ __forceinline__ unsigned xb_add(unsigned* p, unsigned v) { return __hip_atomic_fetch_add(p, v, __ATOMIC_RELAXED, __HIP_MEMORY_SCOPE_AGENT); }
; __device__ __forceinline__ unsigned xb_xcc_id() { return (unsigned)__builtin_amdgcn_s_getreg((3 << 11) | 20) & 0xFu; }
; __device__ __forceinline__ XcdBarrier xcd_barrier_post(unsigned* bar, volatile LAS unsigned* st) {
;   XcdBarrier b; b.bar = bar; b.x = xb_xcc_id(); b.st = st;
;   if (threadIdx.x == 0) (void)xb_add(&bar[XB_XCNT(b.x)], 1u);
;   return b;
; }
.LBB0_76:
	s_or_b64 exec, exec, s[6:7]
	s_barrier
	s_getreg_b32 s4, hwreg(HW_REG_XCC_ID, 0, 4)
	s_and_b32 s4, s4, 15
	v_writelane_b32 v229, s4, 26
	s_mov_b64 s[6:7], exec
	v_readlane_b32 s8, v230, 3
	v_readlane_b32 s9, v230, 4
	s_and_b64 s[8:9], s[6:7], s[8:9]
	s_mov_b64 exec, s[8:9]
	s_cbranch_execz .LBB0_79
	s_mov_b64 s[8:9], exec
	v_mbcnt_lo_u32_b32 v0, s8, 0
	v_mbcnt_hi_u32_b32 v0, s9, v0
	v_cmp_eq_u32_e32 vcc, 0, v0
	s_and_b64 s[10:11], exec, vcc
	s_mov_b64 exec, s[10:11]
	s_cbranch_execz .LBB0_79
	s_getreg_b32 s10, hwreg(HW_REG_HW_ID)
	v_readlane_b32 s4, v229, 26
	s_lshr_b32 s10, s10, 8
	s_and_b32 s11, s10, 0xff
	s_and_b32 s12, s11, 0x90
	s_nop 0
	s_nop 0
	s_and_b32 s13, s11, 15
	s_lshr_b32 s14, s11, 5
	s_and_b32 s14, s14, 3
	s_lshl_b32 s14, s14, 4
	s_or_b32 s13, s13, s14
	s_cmp_eq_u32 s12, 0
	s_cselect_b32 s15, 1, 0
	s_cmp_lg_u32 s13, 0
	s_cselect_b32 s14, 1, 0
	s_and_b32 s15, s15, s14
	s_cmp_lt_u32 s4, 8
	s_cselect_b32 s14, 1, 0
	s_and_b32 s15, s15, s14
	s_add_u32 s14, s4, 8
	s_lshl_b32 s14, s14, 6
	s_add_u32 s14, s14, 0x900
	s_add_u32 s14, s14, s13
	s_lshl_b32 s14, s14, 2
	s_cmp_lg_u32 s15, 0
	s_cselect_b32 s14, s14, 0
	s_nop 0
	v_writelane_b32 v229, s14, 58
	s_cbranch_scc0 .Lxb_noreg
	v_mov_b32_e32 v2, s14
	v_mov_b32_e32 v4, 0x10000
	global_atomic_add v3, v2, v4, s[34:35] sc0
	s_waitcnt vmcnt(0)
